# code placement: gate/up K-loop shifted by 4 bytes (pad before the loop head, 4 more after the loop so later code keeps its 8-byte phase)
# baseline (speedup 1.0000x reference)
; #define PG8_STAGE(bufoff, gbase, voff) do { _Pragma("unroll") for (int _i = 0; _i < 2; ++_i) \
;         __builtin_amdgcn_global_load_lds((const unsigned*)((const char*)(gbase) + (voff)[_i]), (PG8_LAS unsigned*)(lds + (bufoff) + ldsw + _i * 8192), 16, 0, 0); } while (0)
; #define PG8_LDA(dst, b, h) do { _Pragma("unroll") for (int m = 0; m < 4; ++m) _Pragma("unroll") for (int k = 0; k < 2; ++k) dst[m][k] = *(const PG8_LAS bf16x8*)(lds + PG8_SA(b, h) + aoff + m * 2048 + k * 1024); } while (0)
; #define PG8_LDB(dst, b, h) do { _Pragma("unroll") for (int n = 0; n < 2; ++n) _Pragma("unroll") for (int k = 0; k < 2; ++k) dst[n][k] = *(const PG8_LAS bf16x8*)(lds + PG8_SB(b, h) + boff + n * 2048 + k * 1024); } while (0)
; #define PG8_WAIT_V(n) asm volatile("s_waitcnt vmcnt(" #n ")" ::: "memory")
; #define PG8_WAIT_L(n) asm volatile("s_waitcnt lgkmcnt(" #n ")" ::: "memory")
; #define PG8_BAR __builtin_amdgcn_s_barrier()
; template <class Epi, class Sched, bool ALIGN_EPI = false, bool SP2 = false>
; __device__ __forceinline__ void gemm_phase(PG8_LAS unsigned char* lds, const Gemm g, const Sched& S, const Epi& E, int tid_in) {
;     ...
;         const bool has_next = S.next(ui + 1, nxt);
;         const char* nA = has_next ? (const char*)g.A + (size_t)nxt.pm * tstep : cA; const char* nB = has_next ? (const char*)g.Bt + (size_t)nxt.pn * tstep : cB;
;         for (int t = 0; t < nt; t += 2) {
;             const bool last = (t == nt - 2);
;             const char* a1 = cA + (size_t)(t + 1) * kstep;
;             const char* a2 = last ? nA : cA + (size_t)(t + 2) * kstep; const char* b2 = last ? nB : cB + (size_t)(t + 2) * kstep;
;             const char* a3 = a2 + kstep; const char* b3 = b2 + kstep;
;             if (last && has_next) S.a_ready(nxt);
;             if constexpr (SP2) {
;             PG8_LDB(B0, 0, 0); PG8_LDB(B1, 0, 1); PG8_SCHED; PG8_LDA(At, 0, 0); PG8_STAGE(PG8_SA(1, 1), a1 + hstep, voffA);
;             PG8_WAIT_V(8); PG8_WAIT_L(0); PG8_BAR; PG8_MMA(0, 0, At, B0); PG8_MMA(0, 1, At, B1); PG8_BAR; PG8_SCHED;
;     ...
; #pragma unroll
;         for (int a = 0; a < 2; ++a)
; #pragma unroll
;             for (int b = 0; b < 2; ++b)
; #pragma unroll
;                 for (int m = 0; m < 4; ++m)
; #pragma unroll
;                     for (int n = 0; n < 2; ++n) acc[a][b][m][n] = (f32x4){0.f, 0.f, 0.f, 0.f};
;         cur = nxt; cA = nA; cB = nB; ++ui;
.LBB0_478:
	s_ashr_i32 s71, s70, 31
	s_lshl_b64 s[48:49], s[70:71], 20
	s_add_u32 s48, s51, s48
	s_addc_u32 s49, s64, s49
	s_and_b64 s[54:55], s[12:13], exec
	s_cselect_b32 s71, s49, s57
	s_cselect_b32 vcc_lo, s48, s56
	s_ashr_i32 s59, s58, 31
	s_lshl_b64 s[54:55], s[58:59], 20
	s_add_u32 s54, s65, s54
	s_addc_u32 s55, s66, s55
	s_and_b64 s[62:63], s[12:13], exec
	s_cselect_b32 s59, s55, s61
	s_cselect_b32 vcc_hi, s54, s60
	s_add_u32 s56, s56, 0x80080
	s_addc_u32 s57, s57, 0
	s_add_u32 s47, s60, 0x100
	v_mov_b32_e32 v0, 0
	s_addc_u32 s77, s61, 0
	s_mov_b32 s82, -2
	v_mov_b32_e32 v1, v0
	v_mov_b32_e32 v2, v0
	v_mov_b32_e32 v3, v0
	v_mov_b32_e32 v8, v0
	v_mov_b32_e32 v9, v0
	v_mov_b32_e32 v10, v0
	v_mov_b32_e32 v11, v0
	v_mov_b32_e32 v20, v0
	v_mov_b32_e32 v21, v0
	v_mov_b32_e32 v22, v0
	v_mov_b32_e32 v23, v0
	v_mov_b32_e32 v28, v0
	v_mov_b32_e32 v29, v0
	v_mov_b32_e32 v30, v0
	v_mov_b32_e32 v31, v0
	v_mov_b32_e32 v38, v0
	v_mov_b32_e32 v39, v0
	v_mov_b32_e32 v40, v0
	v_mov_b32_e32 v41, v0
	v_mov_b32_e32 v46, v0
	v_mov_b32_e32 v47, v0
	v_mov_b32_e32 v48, v0
	v_mov_b32_e32 v49, v0
	v_mov_b32_e32 v58, v0
	v_mov_b32_e32 v59, v0
	v_mov_b32_e32 v60, v0
	v_mov_b32_e32 v61, v0
	v_mov_b32_e32 v62, v0
	v_mov_b32_e32 v63, v0
	v_mov_b32_e32 v64, v0
	v_mov_b32_e32 v65, v0
	v_mov_b32_e32 v4, v0
	v_mov_b32_e32 v5, v0
	v_mov_b32_e32 v6, v0
	v_mov_b32_e32 v7, v0
	v_mov_b32_e32 v16, v0
	v_mov_b32_e32 v17, v0
	v_mov_b32_e32 v18, v0
	v_mov_b32_e32 v19, v0
	v_mov_b32_e32 v12, v0
	v_mov_b32_e32 v13, v0
	v_mov_b32_e32 v14, v0
	v_mov_b32_e32 v15, v0
	v_mov_b32_e32 v24, v0
	v_mov_b32_e32 v25, v0
	v_mov_b32_e32 v26, v0
	v_mov_b32_e32 v27, v0
	v_mov_b32_e32 v34, v0
	v_mov_b32_e32 v35, v0
	v_mov_b32_e32 v36, v0
	v_mov_b32_e32 v37, v0
	v_mov_b32_e32 v42, v0
	v_mov_b32_e32 v43, v0
	v_mov_b32_e32 v44, v0
	v_mov_b32_e32 v45, v0
	v_mov_b32_e32 v50, v0
	v_mov_b32_e32 v51, v0
	v_mov_b32_e32 v52, v0
	v_mov_b32_e32 v53, v0
	v_mov_b32_e32 v54, v0
	v_mov_b32_e32 v55, v0
	v_mov_b32_e32 v56, v0
	v_mov_b32_e32 v57, v0
	v_mov_b32_e32 v82, v0
	v_mov_b32_e32 v83, v0
	v_mov_b32_e32 v84, v0
	v_mov_b32_e32 v85, v0
	v_mov_b32_e32 v106, v0
	v_mov_b32_e32 v107, v0
	v_mov_b32_e32 v108, v0
	v_mov_b32_e32 v109, v0
	v_mov_b32_e32 v118, v0
	v_mov_b32_e32 v119, v0
	v_mov_b32_e32 v120, v0
	v_mov_b32_e32 v121, v0
	v_mov_b32_e32 v126, v0
	v_mov_b32_e32 v127, v0
	v_mov_b32_e32 v128, v0
	v_mov_b32_e32 v129, v0
	v_mov_b32_e32 v134, v0
	v_mov_b32_e32 v135, v0
	v_mov_b32_e32 v136, v0
	v_mov_b32_e32 v137, v0
	v_mov_b32_e32 v142, v0
	v_mov_b32_e32 v143, v0
	v_mov_b32_e32 v144, v0
	v_mov_b32_e32 v145, v0
	v_mov_b32_e32 v154, v0
	v_mov_b32_e32 v155, v0
	v_mov_b32_e32 v156, v0
	v_mov_b32_e32 v157, v0
	v_mov_b32_e32 v158, v0
	v_mov_b32_e32 v159, v0
	v_mov_b32_e32 v160, v0
	v_mov_b32_e32 v161, v0
	v_mov_b32_e32 v98, v0
	v_mov_b32_e32 v99, v0
	v_mov_b32_e32 v100, v0
	v_mov_b32_e32 v101, v0
	v_mov_b32_e32 v114, v0
	v_mov_b32_e32 v115, v0
	v_mov_b32_e32 v116, v0
	v_mov_b32_e32 v117, v0
	v_mov_b32_e32 v110, v0
	v_mov_b32_e32 v111, v0
	v_mov_b32_e32 v112, v0
	v_mov_b32_e32 v113, v0
	v_mov_b32_e32 v122, v0
	v_mov_b32_e32 v123, v0
	v_mov_b32_e32 v124, v0
	v_mov_b32_e32 v125, v0
	v_mov_b32_e32 v130, v0
	v_mov_b32_e32 v131, v0
	v_mov_b32_e32 v132, v0
	v_mov_b32_e32 v133, v0
	v_mov_b32_e32 v138, v0
	v_mov_b32_e32 v139, v0
	v_mov_b32_e32 v140, v0
	v_mov_b32_e32 v141, v0
	v_mov_b32_e32 v146, v0
	v_mov_b32_e32 v147, v0
	v_mov_b32_e32 v148, v0
	v_mov_b32_e32 v149, v0
	v_mov_b32_e32 v150, v0
	v_mov_b32_e32 v151, v0
	v_mov_b32_e32 v152, v0
	v_mov_b32_e32 v153, v0
	s_nop 0
.LBB0_479:
	s_add_u32 s16, s56, 0xfff80080
	s_addc_u32 s17, s57, -1
	s_add_i32 s18, 0, 0x10000
	s_cmp_eq_u32 s82, 28
	s_cselect_b32 s63, s71, s17
	s_cselect_b32 s62, vcc_lo, s16
	s_cselect_b32 s61, s59, s77
	s_cselect_b32 s60, vcc_hi, s47
	s_add_i32 s19, 0, 0x14000
	v_add_u32_e32 v78, s18, v172
	v_add_u32_e32 v102, s19, v172
	ds_read_b128 v[66:69], v78
	ds_read_b128 v[70:73], v78 offset:1024
	ds_read_b128 v[74:77], v78 offset:2048
	ds_read_b128 v[78:81], v78 offset:3072
	ds_read_b128 v[86:89], v102
	ds_read_b128 v[90:93], v102 offset:1024
	ds_read_b128 v[94:97], v102 offset:2048
	ds_read_b128 v[102:105], v102 offset:3072
	v_lshl_add_u64 v[196:197], s[56:57], 0, v[192:193]
	s_add_i32 m0, s68, 0xc000
	ds_read_b128 v[162:165], v217
	ds_read_b128 v[166:169], v217 offset:1024
	ds_read_b128 v[220:223], v217 offset:2048
	ds_read_b128 v[224:227], v217 offset:3072
	ds_read_b128 v[228:231], v217 offset:4096
	ds_read_b128 v[232:235], v217 offset:5120
	ds_read_b128 v[236:239], v217 offset:6144
	ds_read_b128 v[240:243], v217 offset:7168
	global_load_lds_dwordx4 v[196:197], off
	v_lshl_add_u64 v[196:197], s[56:57], 0, v[194:195]
	s_add_i32 m0, s68, 0xe000
	s_nop 0
	global_load_lds_dwordx4 v[196:197], off
	s_waitcnt vmcnt(8)
	s_waitcnt lgkmcnt(0)
	s_setprio 1
	s_barrier
; #define PG8_STAGE(bufoff, gbase, voff) do { _Pragma("unroll") for (int _i = 0; _i < 2; ++_i) \
;         __builtin_amdgcn_global_load_lds((const unsigned*)((const char*)(gbase) + (voff)[_i]), (PG8_LAS unsigned*)(lds + (bufoff) + ldsw + _i * 8192), 16, 0, 0); } while (0)
; #define PG8_LDA(dst, b, h) do { _Pragma("unroll") for (int m = 0; m < 4; ++m) _Pragma("unroll") for (int k = 0; k < 2; ++k) dst[m][k] = *(const PG8_LAS bf16x8*)(lds + PG8_SA(b, h) + aoff + m * 2048 + k * 1024); } while (0)
; #define PG8_LDB(dst, b, h) do { _Pragma("unroll") for (int n = 0; n < 2; ++n) _Pragma("unroll") for (int k = 0; k < 2; ++k) dst[n][k] = *(const PG8_LAS bf16x8*)(lds + PG8_SB(b, h) + boff + n * 2048 + k * 1024); } while (0)
; #define PG8_MMA(ai, bj, At, Bt) do { __builtin_amdgcn_s_setprio(1); _Pragma("unroll") for (int m = 0; m < 4; ++m) _Pragma("unroll") for (int n = 0; n < 2; ++n) _Pragma("unroll") for (int k = 0; k < 2; ++k) \
;         acc[ai][bj][m][n] = __builtin_amdgcn_mfma_f32_16x16x32_bf16(Bt[n][k], At[m][k], acc[ai][bj][m][n], 0, 0, 0); __builtin_amdgcn_s_setprio(0); } while (0)
; #define PG8_WAIT_V(n) asm volatile("s_waitcnt vmcnt(" #n ")" ::: "memory")
; #define PG8_WAIT_L(n) asm volatile("s_waitcnt lgkmcnt(" #n ")" ::: "memory")
; #define PG8_BAR __builtin_amdgcn_s_barrier()
; #define PG8_SCHED __builtin_amdgcn_sched_barrier(0)
; template <class Epi, class Sched, bool ALIGN_EPI = false, bool SP2 = false>
; __device__ __forceinline__ void gemm_phase(PG8_LAS unsigned char* lds, const Gemm g, const Sched& S, const Epi& E, int tid_in) {
;     ...
;             if constexpr (SP2) {
;             PG8_LDB(B0, 0, 0); PG8_LDB(B1, 0, 1); PG8_SCHED; PG8_LDA(At, 0, 0); PG8_STAGE(PG8_SA(1, 1), a1 + hstep, voffA);
;             PG8_WAIT_V(8); PG8_WAIT_L(0); PG8_BAR; PG8_MMA(0, 0, At, B0); PG8_MMA(0, 1, At, B1); PG8_BAR; PG8_SCHED;
;             PG8_LDA(At, 0, 1); PG8_STAGE(PG8_SB(0, 0), b2, voffB); PG8_STAGE(PG8_SB(0, 1), b2 + hstep, voffB); PG8_STAGE(PG8_SA(0, 0), a2, voffA);
;             PG8_WAIT_V(8); PG8_WAIT_L(0); PG8_BAR; PG8_MMA(1, 0, At, B0); PG8_MMA(1, 1, At, B1); PG8_BAR; PG8_SCHED;
	v_mfma_f32_16x16x32_bf16 v[150:153], v[66:69], v[162:165], v[150:153]
	v_mfma_f32_16x16x32_bf16 v[146:149], v[74:77], v[162:165], v[146:149]
	v_mfma_f32_16x16x32_bf16 v[138:141], v[66:69], v[220:223], v[138:141]
	v_mfma_f32_16x16x32_bf16 v[130:133], v[74:77], v[220:223], v[130:133]
	v_mfma_f32_16x16x32_bf16 v[122:125], v[66:69], v[228:231], v[122:125]
	v_mfma_f32_16x16x32_bf16 v[110:113], v[74:77], v[228:231], v[110:113]
	v_mfma_f32_16x16x32_bf16 v[114:117], v[66:69], v[236:239], v[114:117]
	v_mfma_f32_16x16x32_bf16 v[98:101], v[74:77], v[236:239], v[98:101]
	v_mfma_f32_16x16x32_bf16 v[150:153], v[70:73], v[166:169], v[150:153]
	v_mfma_f32_16x16x32_bf16 v[146:149], v[78:81], v[166:169], v[146:149]
	v_mfma_f32_16x16x32_bf16 v[138:141], v[70:73], v[224:227], v[138:141]
	v_mfma_f32_16x16x32_bf16 v[130:133], v[78:81], v[224:227], v[130:133]
	v_mfma_f32_16x16x32_bf16 v[122:125], v[70:73], v[232:235], v[122:125]
	v_mfma_f32_16x16x32_bf16 v[110:113], v[78:81], v[232:235], v[110:113]
	v_mfma_f32_16x16x32_bf16 v[114:117], v[70:73], v[240:243], v[114:117]
	v_mfma_f32_16x16x32_bf16 v[98:101], v[78:81], v[240:243], v[98:101]
	v_mfma_f32_16x16x32_bf16 v[158:161], v[86:89], v[162:165], v[158:161]
	v_mfma_f32_16x16x32_bf16 v[154:157], v[94:97], v[162:165], v[154:157]
	v_mfma_f32_16x16x32_bf16 v[142:145], v[86:89], v[220:223], v[142:145]
	v_mfma_f32_16x16x32_bf16 v[134:137], v[94:97], v[220:223], v[134:137]
	v_mfma_f32_16x16x32_bf16 v[126:129], v[86:89], v[228:231], v[126:129]
	v_mfma_f32_16x16x32_bf16 v[118:121], v[94:97], v[228:231], v[118:121]
	v_mfma_f32_16x16x32_bf16 v[106:109], v[86:89], v[236:239], v[106:109]
	v_mfma_f32_16x16x32_bf16 v[82:85], v[94:97], v[236:239], v[82:85]
	v_mfma_f32_16x16x32_bf16 v[158:161], v[90:93], v[166:169], v[158:161]
	v_mfma_f32_16x16x32_bf16 v[154:157], v[102:105], v[166:169], v[154:157]
	v_mfma_f32_16x16x32_bf16 v[142:145], v[90:93], v[224:227], v[142:145]
	v_mfma_f32_16x16x32_bf16 v[134:137], v[102:105], v[224:227], v[134:137]
	v_mfma_f32_16x16x32_bf16 v[126:129], v[90:93], v[232:235], v[126:129]
	v_mfma_f32_16x16x32_bf16 v[118:121], v[102:105], v[232:235], v[118:121]
	v_mfma_f32_16x16x32_bf16 v[106:109], v[90:93], v[240:243], v[106:109]
	v_mfma_f32_16x16x32_bf16 v[82:85], v[102:105], v[240:243], v[82:85]
	s_setprio 0
	s_barrier
	s_add_i32 s16, s18, s67
	v_lshl_add_u64 v[196:197], s[60:61], 0, v[32:33]
	s_mov_b32 m0, s16
	ds_read_b128 v[162:165], v217 offset:16384
	ds_read_b128 v[166:169], v217 offset:17408
	ds_read_b128 v[220:223], v217 offset:18432
	ds_read_b128 v[224:227], v217 offset:19456
	ds_read_b128 v[228:231], v217 offset:20480
	ds_read_b128 v[232:235], v217 offset:21504
	ds_read_b128 v[236:239], v217 offset:22528
	ds_read_b128 v[240:243], v217 offset:23552
	global_load_lds_dwordx4 v[196:197], off
	s_add_i32 m0, s16, 0x2000
	s_add_u32 s16, s60, 0x80000
	v_lshl_add_u64 v[244:245], s[60:61], 0, v[186:187]
	s_addc_u32 s17, s61, 0
	s_add_i32 s18, s19, s67
	global_load_lds_dwordx4 v[244:245], off
	v_lshl_add_u64 v[246:247], s[16:17], 0, v[32:33]
	s_mov_b32 m0, s18
	v_lshl_add_u64 v[248:249], s[62:63], 0, v[188:189]
	global_load_lds_dwordx4 v[246:247], off
	v_lshl_add_u64 v[246:247], s[16:17], 0, v[186:187]
	s_add_i32 m0, s18, 0x2000
	s_nop 0
	global_load_lds_dwordx4 v[246:247], off
	v_lshl_add_u64 v[246:247], s[62:63], 0, v[190:191]
	s_mov_b32 m0, s68
	s_nop 0
	global_load_lds_dwordx4 v[246:247], off
	s_mov_b32 m0, s14
	s_nop 0
	global_load_lds_dwordx4 v[248:249], off
	s_waitcnt vmcnt(8)
	s_waitcnt lgkmcnt(0)
	s_setprio 1
	s_barrier
	v_mfma_f32_16x16x32_bf16 v[54:57], v[66:69], v[162:165], v[54:57]
	v_mfma_f32_16x16x32_bf16 v[50:53], v[74:77], v[162:165], v[50:53]
	v_mfma_f32_16x16x32_bf16 v[42:45], v[66:69], v[220:223], v[42:45]
	v_mfma_f32_16x16x32_bf16 v[34:37], v[74:77], v[220:223], v[34:37]
	v_mfma_f32_16x16x32_bf16 v[24:27], v[66:69], v[228:231], v[24:27]
	v_mfma_f32_16x16x32_bf16 v[12:15], v[74:77], v[228:231], v[12:15]
	v_mfma_f32_16x16x32_bf16 v[16:19], v[66:69], v[236:239], v[16:19]
	v_mfma_f32_16x16x32_bf16 v[4:7], v[74:77], v[236:239], v[4:7]
	v_mfma_f32_16x16x32_bf16 v[54:57], v[70:73], v[166:169], v[54:57]
	v_mfma_f32_16x16x32_bf16 v[50:53], v[78:81], v[166:169], v[50:53]
	v_mfma_f32_16x16x32_bf16 v[42:45], v[70:73], v[224:227], v[42:45]
	v_mfma_f32_16x16x32_bf16 v[34:37], v[78:81], v[224:227], v[34:37]
	v_mfma_f32_16x16x32_bf16 v[24:27], v[70:73], v[232:235], v[24:27]
	v_mfma_f32_16x16x32_bf16 v[12:15], v[78:81], v[232:235], v[12:15]
	v_mfma_f32_16x16x32_bf16 v[16:19], v[70:73], v[240:243], v[16:19]
	v_mfma_f32_16x16x32_bf16 v[4:7], v[78:81], v[240:243], v[4:7]
	v_mfma_f32_16x16x32_bf16 v[62:65], v[86:89], v[162:165], v[62:65]
	v_mfma_f32_16x16x32_bf16 v[58:61], v[94:97], v[162:165], v[58:61]
	v_mfma_f32_16x16x32_bf16 v[46:49], v[86:89], v[220:223], v[46:49]
	v_mfma_f32_16x16x32_bf16 v[38:41], v[94:97], v[220:223], v[38:41]
	v_mfma_f32_16x16x32_bf16 v[28:31], v[86:89], v[228:231], v[28:31]
	v_mfma_f32_16x16x32_bf16 v[20:23], v[94:97], v[228:231], v[20:23]
	v_mfma_f32_16x16x32_bf16 v[8:11], v[86:89], v[236:239], v[8:11]
	v_mfma_f32_16x16x32_bf16 v[0:3], v[94:97], v[236:239], v[0:3]
	v_mfma_f32_16x16x32_bf16 v[62:65], v[90:93], v[166:169], v[62:65]
	v_mfma_f32_16x16x32_bf16 v[58:61], v[102:105], v[166:169], v[58:61]
	v_mfma_f32_16x16x32_bf16 v[46:49], v[90:93], v[224:227], v[46:49]
	v_mfma_f32_16x16x32_bf16 v[38:41], v[102:105], v[224:227], v[38:41]
	v_mfma_f32_16x16x32_bf16 v[28:31], v[90:93], v[232:235], v[28:31]
	v_mfma_f32_16x16x32_bf16 v[20:23], v[102:105], v[232:235], v[20:23]
	v_mfma_f32_16x16x32_bf16 v[8:11], v[90:93], v[240:243], v[8:11]
	v_mfma_f32_16x16x32_bf16 v[0:3], v[102:105], v[240:243], v[0:3]
	s_setprio 0
	s_barrier
; #define PG8_STAGE(bufoff, gbase, voff) do { _Pragma("unroll") for (int _i = 0; _i < 2; ++_i) \
;         __builtin_amdgcn_global_load_lds((const unsigned*)((const char*)(gbase) + (voff)[_i]), (PG8_LAS unsigned*)(lds + (bufoff) + ldsw + _i * 8192), 16, 0, 0); } while (0)
; #define PG8_LDA(dst, b, h) do { _Pragma("unroll") for (int m = 0; m < 4; ++m) _Pragma("unroll") for (int k = 0; k < 2; ++k) dst[m][k] = *(const PG8_LAS bf16x8*)(lds + PG8_SA(b, h) + aoff + m * 2048 + k * 1024); } while (0)
; #define PG8_LDB(dst, b, h) do { _Pragma("unroll") for (int n = 0; n < 2; ++n) _Pragma("unroll") for (int k = 0; k < 2; ++k) dst[n][k] = *(const PG8_LAS bf16x8*)(lds + PG8_SB(b, h) + boff + n * 2048 + k * 1024); } while (0)
; #define PG8_MMA(ai, bj, At, Bt) do { __builtin_amdgcn_s_setprio(1); _Pragma("unroll") for (int m = 0; m < 4; ++m) _Pragma("unroll") for (int n = 0; n < 2; ++n) _Pragma("unroll") for (int k = 0; k < 2; ++k) \
;         acc[ai][bj][m][n] = __builtin_amdgcn_mfma_f32_16x16x32_bf16(Bt[n][k], At[m][k], acc[ai][bj][m][n], 0, 0, 0); __builtin_amdgcn_s_setprio(0); } while (0)
; #define PG8_WAIT_V(n) asm volatile("s_waitcnt vmcnt(" #n ")" ::: "memory")
; #define PG8_WAIT_L(n) asm volatile("s_waitcnt lgkmcnt(" #n ")" ::: "memory")
; #define PG8_BAR __builtin_amdgcn_s_barrier()
; #define PG8_SCHED __builtin_amdgcn_sched_barrier(0)
; template <class Epi, class Sched, bool ALIGN_EPI = false, bool SP2 = false>
; __device__ __forceinline__ void gemm_phase(PG8_LAS unsigned char* lds, const Gemm g, const Sched& S, const Epi& E, int tid_in) {
;     ...
;             PG8_LDB(B0, 1, 0); PG8_LDB(B1, 1, 1); PG8_SCHED; PG8_LDA(At, 1, 0); PG8_STAGE(PG8_SA(0, 1), a2 + hstep, voffA);
;             PG8_WAIT_V(8); PG8_WAIT_L(0); PG8_BAR; PG8_MMA(0, 0, At, B0); PG8_MMA(0, 1, At, B1); PG8_BAR; PG8_SCHED;
	s_add_i32 s18, 0, 0x18000
	s_add_i32 s19, 0, 0x1c000
	v_add_u32_e32 v78, s18, v172
	v_add_u32_e32 v102, s19, v172
	ds_read_b128 v[66:69], v78
	ds_read_b128 v[70:73], v78 offset:1024
	ds_read_b128 v[74:77], v78 offset:2048
	ds_read_b128 v[78:81], v78 offset:3072
	ds_read_b128 v[86:89], v102
	ds_read_b128 v[90:93], v102 offset:1024
	ds_read_b128 v[94:97], v102 offset:2048
	ds_read_b128 v[102:105], v102 offset:3072
	s_add_u32 s16, s62, 0x80000
	s_addc_u32 s17, s63, 0
	s_mov_b32 m0, s15
	v_lshl_add_u64 v[250:251], s[16:17], 0, v[190:191]
	ds_read_b128 v[162:165], v217 offset:32768
	ds_read_b128 v[166:169], v217 offset:33792
	ds_read_b128 v[220:223], v217 offset:34816
	ds_read_b128 v[224:227], v217 offset:35840
	ds_read_b128 v[228:231], v217 offset:36864
	ds_read_b128 v[232:235], v217 offset:37888
	ds_read_b128 v[236:239], v217 offset:38912
	ds_read_b128 v[240:243], v217 offset:39936
	global_load_lds_dwordx4 v[250:251], off
	v_lshl_add_u64 v[250:251], s[16:17], 0, v[188:189]
	s_mov_b32 m0, s4
	s_nop 0
	global_load_lds_dwordx4 v[250:251], off
	s_waitcnt vmcnt(8)
	s_waitcnt lgkmcnt(0)
	s_setprio 1
	s_barrier
	v_mfma_f32_16x16x32_bf16 v[150:153], v[66:69], v[162:165], v[150:153]
	v_mfma_f32_16x16x32_bf16 v[146:149], v[74:77], v[162:165], v[146:149]
	v_mfma_f32_16x16x32_bf16 v[138:141], v[66:69], v[220:223], v[138:141]
	v_mfma_f32_16x16x32_bf16 v[130:133], v[74:77], v[220:223], v[130:133]
	v_mfma_f32_16x16x32_bf16 v[122:125], v[66:69], v[228:231], v[122:125]
	v_mfma_f32_16x16x32_bf16 v[110:113], v[74:77], v[228:231], v[110:113]
	v_mfma_f32_16x16x32_bf16 v[114:117], v[66:69], v[236:239], v[114:117]
	v_mfma_f32_16x16x32_bf16 v[98:101], v[74:77], v[236:239], v[98:101]
	v_mfma_f32_16x16x32_bf16 v[150:153], v[70:73], v[166:169], v[150:153]
	v_mfma_f32_16x16x32_bf16 v[146:149], v[78:81], v[166:169], v[146:149]
	v_mfma_f32_16x16x32_bf16 v[138:141], v[70:73], v[224:227], v[138:141]
	v_mfma_f32_16x16x32_bf16 v[130:133], v[78:81], v[224:227], v[130:133]
	v_mfma_f32_16x16x32_bf16 v[122:125], v[70:73], v[232:235], v[122:125]
	v_mfma_f32_16x16x32_bf16 v[110:113], v[78:81], v[232:235], v[110:113]
	v_mfma_f32_16x16x32_bf16 v[114:117], v[70:73], v[240:243], v[114:117]
	v_mfma_f32_16x16x32_bf16 v[98:101], v[78:81], v[240:243], v[98:101]
	v_mfma_f32_16x16x32_bf16 v[158:161], v[86:89], v[162:165], v[158:161]
	v_mfma_f32_16x16x32_bf16 v[154:157], v[94:97], v[162:165], v[154:157]
	v_mfma_f32_16x16x32_bf16 v[142:145], v[86:89], v[220:223], v[142:145]
	v_mfma_f32_16x16x32_bf16 v[134:137], v[94:97], v[220:223], v[134:137]
	v_mfma_f32_16x16x32_bf16 v[126:129], v[86:89], v[228:231], v[126:129]
	v_mfma_f32_16x16x32_bf16 v[118:121], v[94:97], v[228:231], v[118:121]
	v_mfma_f32_16x16x32_bf16 v[106:109], v[86:89], v[236:239], v[106:109]
	v_mfma_f32_16x16x32_bf16 v[82:85], v[94:97], v[236:239], v[82:85]
	v_mfma_f32_16x16x32_bf16 v[158:161], v[90:93], v[166:169], v[158:161]
	v_mfma_f32_16x16x32_bf16 v[154:157], v[102:105], v[166:169], v[154:157]
	v_mfma_f32_16x16x32_bf16 v[142:145], v[90:93], v[224:227], v[142:145]
	v_mfma_f32_16x16x32_bf16 v[134:137], v[102:105], v[224:227], v[134:137]
	v_mfma_f32_16x16x32_bf16 v[126:129], v[90:93], v[232:235], v[126:129]
	v_mfma_f32_16x16x32_bf16 v[118:121], v[102:105], v[232:235], v[118:121]
	v_mfma_f32_16x16x32_bf16 v[106:109], v[90:93], v[240:243], v[106:109]
	v_mfma_f32_16x16x32_bf16 v[82:85], v[102:105], v[240:243], v[82:85]
	s_setprio 0
	s_barrier
; #define PG8_STAGE(bufoff, gbase, voff) do { _Pragma("unroll") for (int _i = 0; _i < 2; ++_i) \
;         __builtin_amdgcn_global_load_lds((const unsigned*)((const char*)(gbase) + (voff)[_i]), (PG8_LAS unsigned*)(lds + (bufoff) + ldsw + _i * 8192), 16, 0, 0); } while (0)
; #define PG8_LDA(dst, b, h) do { _Pragma("unroll") for (int m = 0; m < 4; ++m) _Pragma("unroll") for (int k = 0; k < 2; ++k) dst[m][k] = *(const PG8_LAS bf16x8*)(lds + PG8_SA(b, h) + aoff + m * 2048 + k * 1024); } while (0)
; #define PG8_MMA(ai, bj, At, Bt) do { __builtin_amdgcn_s_setprio(1); _Pragma("unroll") for (int m = 0; m < 4; ++m) _Pragma("unroll") for (int n = 0; n < 2; ++n) _Pragma("unroll") for (int k = 0; k < 2; ++k) \
;         acc[ai][bj][m][n] = __builtin_amdgcn_mfma_f32_16x16x32_bf16(Bt[n][k], At[m][k], acc[ai][bj][m][n], 0, 0, 0); __builtin_amdgcn_s_setprio(0); } while (0)
; #define PG8_WAIT_V(n) asm volatile("s_waitcnt vmcnt(" #n ")" ::: "memory")
; #define PG8_WAIT_L(n) asm volatile("s_waitcnt lgkmcnt(" #n ")" ::: "memory")
; #define PG8_BAR __builtin_amdgcn_s_barrier()
; #define PG8_SCHED __builtin_amdgcn_sched_barrier(0)
; template <class Epi, class Sched, bool ALIGN_EPI = false, bool SP2 = false>
; __device__ __forceinline__ void gemm_phase(PG8_LAS unsigned char* lds, const Gemm g, const Sched& S, const Epi& E, int tid_in) {
;     ...
;             PG8_LDA(At, 1, 1); PG8_STAGE(PG8_SB(1, 0), b3, voffB); PG8_STAGE(PG8_SB(1, 1), b3 + hstep, voffB); PG8_STAGE(PG8_SA(1, 0), a3, voffA);
;             PG8_WAIT_V(8); PG8_WAIT_L(0); PG8_BAR; PG8_MMA(1, 0, At, B0); PG8_MMA(1, 1, At, B1); PG8_BAR; PG8_SCHED;
;     ...
;         if constexpr (ALIGN_EPI) { if (wr == 0) PG8_BAR; }
	s_add_i32 s16, s18, s67
	v_lshl_add_u64 v[196:197], v[196:197], 0, s[74:75]
	s_mov_b32 m0, s16
	ds_read_b128 v[162:165], v217 offset:49152
	ds_read_b128 v[166:169], v217 offset:50176
	ds_read_b128 v[220:223], v217 offset:51200
	ds_read_b128 v[224:227], v217 offset:52224
	ds_read_b128 v[228:231], v217 offset:53248
	ds_read_b128 v[232:235], v217 offset:54272
	ds_read_b128 v[236:239], v217 offset:55296
	ds_read_b128 v[240:243], v217 offset:56320
	global_load_lds_dwordx4 v[196:197], off
	s_add_i32 m0, s16, 0x2000
	s_add_u32 s16, s60, 0x80080
	v_lshl_add_u64 v[196:197], v[244:245], 0, s[74:75]
	s_addc_u32 s17, s61, 0
	s_add_i32 s18, s19, s67
	global_load_lds_dwordx4 v[196:197], off
	v_lshl_add_u64 v[196:197], s[16:17], 0, v[32:33]
	s_mov_b32 m0, s18
	s_nop 0
	global_load_lds_dwordx4 v[196:197], off
	v_lshl_add_u64 v[196:197], s[16:17], 0, v[186:187]
	s_add_i32 m0, s18, 0x2000
	s_nop 0
	global_load_lds_dwordx4 v[196:197], off
	v_lshl_add_u64 v[196:197], v[246:247], 0, s[74:75]
	s_mov_b32 m0, s85
	s_nop 0
	global_load_lds_dwordx4 v[196:197], off
	v_lshl_add_u64 v[196:197], v[248:249], 0, s[74:75]
	s_mov_b32 m0, s80
	s_nop 0
	global_load_lds_dwordx4 v[196:197], off
	s_waitcnt vmcnt(8)
	s_waitcnt lgkmcnt(0)
	s_setprio 1
	s_barrier
	v_mfma_f32_16x16x32_bf16 v[54:57], v[66:69], v[162:165], v[54:57]
	v_mfma_f32_16x16x32_bf16 v[50:53], v[74:77], v[162:165], v[50:53]
	v_mfma_f32_16x16x32_bf16 v[42:45], v[66:69], v[220:223], v[42:45]
	v_mfma_f32_16x16x32_bf16 v[34:37], v[74:77], v[220:223], v[34:37]
	v_mfma_f32_16x16x32_bf16 v[24:27], v[66:69], v[228:231], v[24:27]
	v_mfma_f32_16x16x32_bf16 v[12:15], v[74:77], v[228:231], v[12:15]
	v_mfma_f32_16x16x32_bf16 v[16:19], v[66:69], v[236:239], v[16:19]
	v_mfma_f32_16x16x32_bf16 v[4:7], v[74:77], v[236:239], v[4:7]
	v_mfma_f32_16x16x32_bf16 v[54:57], v[70:73], v[166:169], v[54:57]
	v_mfma_f32_16x16x32_bf16 v[50:53], v[78:81], v[166:169], v[50:53]
	v_mfma_f32_16x16x32_bf16 v[42:45], v[70:73], v[224:227], v[42:45]
	v_mfma_f32_16x16x32_bf16 v[34:37], v[78:81], v[224:227], v[34:37]
	v_mfma_f32_16x16x32_bf16 v[24:27], v[70:73], v[232:235], v[24:27]
	v_mfma_f32_16x16x32_bf16 v[12:15], v[78:81], v[232:235], v[12:15]
	v_mfma_f32_16x16x32_bf16 v[16:19], v[70:73], v[240:243], v[16:19]
	v_mfma_f32_16x16x32_bf16 v[4:7], v[78:81], v[240:243], v[4:7]
	v_mfma_f32_16x16x32_bf16 v[62:65], v[86:89], v[162:165], v[62:65]
	v_mfma_f32_16x16x32_bf16 v[58:61], v[94:97], v[162:165], v[58:61]
	v_mfma_f32_16x16x32_bf16 v[46:49], v[86:89], v[220:223], v[46:49]
	v_mfma_f32_16x16x32_bf16 v[38:41], v[94:97], v[220:223], v[38:41]
	v_mfma_f32_16x16x32_bf16 v[28:31], v[86:89], v[228:231], v[28:31]
	v_mfma_f32_16x16x32_bf16 v[20:23], v[94:97], v[228:231], v[20:23]
	v_mfma_f32_16x16x32_bf16 v[8:11], v[86:89], v[236:239], v[8:11]
	v_mfma_f32_16x16x32_bf16 v[0:3], v[94:97], v[236:239], v[0:3]
	v_mfma_f32_16x16x32_bf16 v[62:65], v[90:93], v[166:169], v[62:65]
	v_mfma_f32_16x16x32_bf16 v[58:61], v[102:105], v[166:169], v[58:61]
	v_mfma_f32_16x16x32_bf16 v[46:49], v[90:93], v[224:227], v[46:49]
	v_mfma_f32_16x16x32_bf16 v[38:41], v[102:105], v[224:227], v[38:41]
	v_mfma_f32_16x16x32_bf16 v[28:31], v[90:93], v[232:235], v[28:31]
	v_mfma_f32_16x16x32_bf16 v[20:23], v[102:105], v[232:235], v[20:23]
	v_mfma_f32_16x16x32_bf16 v[8:11], v[90:93], v[240:243], v[8:11]
	v_mfma_f32_16x16x32_bf16 v[0:3], v[102:105], v[240:243], v[0:3]
	s_setprio 0
	s_barrier
	s_add_i32 s82, s82, 2
	s_add_u32 s56, s56, 0x100
	s_addc_u32 s57, s57, 0
	s_add_u32 s47, s47, 0x100
	s_addc_u32 s77, s77, 0
	s_cmp_gt_u32 s82, 29
	s_cbranch_scc0 .LBB0_479
	s_nop 0
	s_and_b64 vcc, exec, s[34:35]
	s_cbranch_vccz .LBB0_482
	s_barrier
